# GEMM1: stage next unit's As[1][1]@tile1 at epilogue entry + peeled first K-loop iteration with counted vmcnt(16) waits so epilogue store drain overlaps the next unit's first K-tiles
# baseline (speedup 1.0000x reference)
.LBB0_218:
	s_add_u32 s89, s54, 0x2c00000
	s_addc_u32 s90, s55, 0
	s_add_u32 s4, s54, 0x4c00000
	v_writelane_b32 v251, s4, 29
	s_addc_u32 s4, s55, 0
	s_add_u32 s93, s54, 0x6c00000
	s_addc_u32 s94, s55, 0
	s_add_u32 s68, s54, 0x480000
	v_writelane_b32 v251, s4, 30
	s_addc_u32 s4, s55, 0
	s_add_u32 s14, s54, 0x4c0000
	s_addc_u32 s15, s55, 0
	s_bfe_u32 s95, s96, 0x20006
	v_writelane_b32 v251, s14, 31
	s_mov_b32 s5, s96
	s_lshl_b32 s96, s12, 6
	s_lshl_b32 s10, s95, 5
	v_writelane_b32 v251, s15, 32
	s_cmpk_lt_u32 s5, 0x100
	v_writelane_b32 v251, s10, 33
	s_cselect_b64 s[82:83], -1, 0
	s_cmpk_gt_u32 s5, 0xff
	v_writelane_b32 v251, s5, 34
	s_cselect_b64 s[14:15], -1, 0
	v_writelane_b32 v251, s14, 35
	s_lshl_b32 s97, s95, 7
	s_add_i32 s10, 0, 0x22400
	v_writelane_b32 v251, s15, 36
	s_mov_b32 s63, s61
	s_lshl_b32 s5, s62, 7
	s_add_i32 s11, s10, s97
	s_lshl_b64 s[42:43], s[62:63], 13
	v_writelane_b32 v251, s11, 37
	s_mov_b32 s63, s10
	s_add_i32 s10, s10, s5
	v_writelane_b32 v251, s10, 38
	v_writelane_b32 v251, s5, 39
	s_add_i32 s5, s5, 0
	s_add_i32 s5, s5, 0x22600
	v_writelane_b32 v251, s5, 40
	s_lshl_b32 s65, s95, 4
	s_ashr_i32 s64, s58, 31
	v_readlane_b32 s16, v251, 2
	v_readlane_b32 s17, v251, 3
	s_add_u32 s44, s16, 0x1000
	s_addc_u32 s45, s17, 0
	s_add_u32 s46, s16, 0x2000
	s_mov_b64 s[48:49], 0x80
	s_addc_u32 s47, s17, 0
	v_lshl_add_u64 v[2:3], v[2:3], 0, s[48:49]
	s_add_i32 m0, s79, 0x18000
	s_and_b32 s69, s4, 0xffff
	s_waitcnt vmcnt(2)
	s_barrier
	global_load_lds_dwordx4 v[2:3], off
	s_add_i32 m0, s79, 0x1a000
	s_add_u32 s4, s6, 0x8000
	v_lshl_add_u64 v[0:1], v[0:1], 0, s[48:49]
	s_addc_u32 s5, s7, 0
	s_add_i32 s33, s79, 0x8000
	global_load_lds_dwordx4 v[0:1], off
	v_lshl_add_u64 v[0:1], s[4:5], 0, v[144:145]
	s_mov_b32 m0, s33
	s_add_i32 s56, s79, 0xa000
	global_load_lds_dwordx4 v[0:1], off
	v_lshl_add_u64 v[0:1], s[4:5], 0, v[148:149]
	s_add_u32 s4, s8, 0x40080
	s_mov_b32 m0, s56
	s_addc_u32 s5, s9, 0
	global_load_lds_dwordx4 v[0:1], off
	v_lshl_add_u64 v[0:1], s[4:5], 0, v[146:147]
	s_add_i32 m0, s79, 0x1c000
	v_and_b32_e32 v176, 15, v4
	global_load_lds_dwordx4 v[0:1], off
	v_lshl_add_u64 v[0:1], s[4:5], 0, v[150:151]
	s_add_i32 m0, s79, 0x1e000
	v_lshlrev_b32_e32 v3, 2, v4
	global_load_lds_dwordx4 v[0:1], off
	v_and_b32_e32 v0, 48, v4
	v_and_b32_e32 v1, 0xfffffc00, v6
	v_lshl_add_u32 v2, s12, 13, v1
	v_lshl_or_b32 v0, v176, 6, v0
	v_and_b32_e32 v3, 32, v3
	v_lshl_add_u32 v1, s95, 12, v1
	v_bitop3_b32 v2, v0, v2, v3 bitop3:0xde
	v_bitop3_b32 v178, v0, v1, v3 bitop3:0xde
	v_lshlrev_b32_e32 v0, 9, v5
	v_and_b32_e32 v0, 0x7ffffc00, v0
	v_add3_u32 v0, v0, v7, v8
	v_add_lshl_u32 v152, v0, v9, 1
	v_lshlrev_b32_e32 v0, 9, v10
	v_and_b32_e32 v0, 0x7ffffc00, v0
	v_readlane_b32 s28, v251, 14
	v_readlane_b32 s29, v251, 15
	v_readlane_b32 s30, v251, 16
	v_readlane_b32 s31, v251, 17
	s_waitcnt vmcnt(6)
	s_mov_b64 s[4:5], 0xc000
	v_add3_u32 v0, v0, v11, v12
	s_mov_b32 s71, 0x20000
	s_mov_b32 s70, 0x40000
	s_mov_b64 s[28:29], s[68:69]
	v_lshl_add_u64 v[154:155], v[152:153], 0, s[4:5]
	v_add_lshl_u32 v152, v0, v13, 1
	s_add_i32 s34, 0, 0x10000
	s_add_i32 s35, 0, 0x14000
	s_mov_b64 s[30:31], s[70:71]
	v_ashrrev_i32_e32 v177, 4, v4
	v_lshl_add_u64 v[156:157], v[152:153], 0, s[4:5]
	v_mov_b64_e32 v[158:159], 0x800
	v_mov_b64_e32 v[160:161], 0x7ff
	v_add_u32_e32 v179, s34, v178
	v_add_u32_e32 v180, s35, v178
	v_add_u32_e32 v181, 0, v2
	s_mov_b32 s57, 0xc2fc0000
	v_mov_b32_e32 v182, 0x42800000
	v_not_b32_e32 v183, 63
	v_mov_b32_e32 v184, 0x3db504f3
	s_mov_b32 s91, 0
	s_mov_b32 s66, 0x437f0000
	v_readlane_b32 s18, v251, 4
	v_readlane_b32 s19, v251, 5
	v_readlane_b32 s20, v251, 6
	v_readlane_b32 s21, v251, 7
	v_readlane_b32 s22, v251, 8
	v_readlane_b32 s23, v251, 9
	v_readlane_b32 s24, v251, 10
	v_readlane_b32 s25, v251, 11
	v_readlane_b32 s26, v251, 12
	v_readlane_b32 s27, v251, 13
	s_barrier
	s_mov_b32 s100, 0
	s_branch .LBB0_221

.LBB0_227:
	s_ashr_i32 s69, s68, 31
	s_lshl_b64 s[10:11], s[68:69], 19
	s_add_u32 s72, s52, s10
	s_addc_u32 s73, s53, s11
	s_and_b64 s[10:11], s[4:5], exec
	s_cselect_b32 s18, s73, s7
	s_cselect_b32 s69, s72, s6
	s_ashr_i32 s71, s70, 31
	s_lshl_b64 s[10:11], s[70:71], 19
	s_add_u32 s74, s59, s10
	s_addc_u32 s75, s67, s11
	s_and_b64 s[10:11], s[4:5], exec
	s_cselect_b32 s71, s75, s9
	s_cselect_b32 s77, s74, s8
	s_add_u32 vcc_lo, s8, 0x100
	v_mov_b32_e32 v0, 0
	s_addc_u32 vcc_hi, s9, 0
	s_mov_b32 s92, -2
	v_mov_b32_e32 v1, v0
	v_mov_b32_e32 v2, v0
	v_mov_b32_e32 v3, v0
	v_mov_b32_e32 v4, v0
	v_mov_b32_e32 v5, v0
	v_mov_b32_e32 v6, v0
	v_mov_b32_e32 v7, v0
	v_mov_b32_e32 v16, v0
	v_mov_b32_e32 v17, v0
	v_mov_b32_e32 v18, v0
	v_mov_b32_e32 v19, v0
	v_mov_b32_e32 v20, v0
	v_mov_b32_e32 v21, v0
	v_mov_b32_e32 v22, v0
	v_mov_b32_e32 v23, v0
	v_mov_b32_e32 v32, v0
	v_mov_b32_e32 v33, v0
	v_mov_b32_e32 v34, v0
	v_mov_b32_e32 v35, v0
	v_mov_b32_e32 v36, v0
	v_mov_b32_e32 v37, v0
	v_mov_b32_e32 v38, v0
	v_mov_b32_e32 v39, v0
	v_mov_b32_e32 v48, v0
	v_mov_b32_e32 v49, v0
	v_mov_b32_e32 v50, v0
	v_mov_b32_e32 v51, v0
	v_mov_b32_e32 v52, v0
	v_mov_b32_e32 v53, v0
	v_mov_b32_e32 v54, v0
	v_mov_b32_e32 v55, v0
	v_mov_b32_e32 v8, v0
	v_mov_b32_e32 v9, v0
	v_mov_b32_e32 v10, v0
	v_mov_b32_e32 v11, v0
	v_mov_b32_e32 v12, v0
	v_mov_b32_e32 v13, v0
	v_mov_b32_e32 v14, v0
	v_mov_b32_e32 v15, v0
	v_mov_b32_e32 v24, v0
	v_mov_b32_e32 v25, v0
	v_mov_b32_e32 v26, v0
	v_mov_b32_e32 v27, v0
	v_mov_b32_e32 v28, v0
	v_mov_b32_e32 v29, v0
	v_mov_b32_e32 v30, v0
	v_mov_b32_e32 v31, v0
	v_mov_b32_e32 v40, v0
	v_mov_b32_e32 v41, v0
	v_mov_b32_e32 v42, v0
	v_mov_b32_e32 v43, v0
	v_mov_b32_e32 v44, v0
	v_mov_b32_e32 v45, v0
	v_mov_b32_e32 v46, v0
	v_mov_b32_e32 v47, v0
	v_mov_b32_e32 v56, v0
	v_mov_b32_e32 v57, v0
	v_mov_b32_e32 v58, v0
	v_mov_b32_e32 v59, v0
	v_mov_b32_e32 v60, v0
	v_mov_b32_e32 v61, v0
	v_mov_b32_e32 v62, v0
	v_mov_b32_e32 v63, v0
	v_mov_b32_e32 v64, v0
	v_mov_b32_e32 v65, v0
	v_mov_b32_e32 v66, v0
	v_mov_b32_e32 v67, v0
	v_mov_b32_e32 v68, v0
	v_mov_b32_e32 v69, v0
	v_mov_b32_e32 v70, v0
	v_mov_b32_e32 v71, v0
	v_mov_b32_e32 v80, v0
	v_mov_b32_e32 v81, v0
	v_mov_b32_e32 v82, v0
	v_mov_b32_e32 v83, v0
	v_mov_b32_e32 v84, v0
	v_mov_b32_e32 v85, v0
	v_mov_b32_e32 v86, v0
	v_mov_b32_e32 v87, v0
	v_mov_b32_e32 v96, v0
	v_mov_b32_e32 v97, v0
	v_mov_b32_e32 v98, v0
	v_mov_b32_e32 v99, v0
	v_mov_b32_e32 v100, v0
	v_mov_b32_e32 v101, v0
	v_mov_b32_e32 v102, v0
	v_mov_b32_e32 v103, v0
	v_mov_b32_e32 v112, v0
	v_mov_b32_e32 v113, v0
	v_mov_b32_e32 v114, v0
	v_mov_b32_e32 v115, v0
	v_mov_b32_e32 v116, v0
	v_mov_b32_e32 v117, v0
	v_mov_b32_e32 v118, v0
	v_mov_b32_e32 v119, v0
	v_mov_b32_e32 v72, v0
	v_mov_b32_e32 v73, v0
	v_mov_b32_e32 v74, v0
	v_mov_b32_e32 v75, v0
	v_mov_b32_e32 v76, v0
	v_mov_b32_e32 v77, v0
	v_mov_b32_e32 v78, v0
	v_mov_b32_e32 v79, v0
	v_mov_b32_e32 v88, v0
	v_mov_b32_e32 v89, v0
	v_mov_b32_e32 v90, v0
	v_mov_b32_e32 v91, v0
	v_mov_b32_e32 v92, v0
	v_mov_b32_e32 v93, v0
	v_mov_b32_e32 v94, v0
	v_mov_b32_e32 v95, v0
	v_mov_b32_e32 v104, v0
	v_mov_b32_e32 v105, v0
	v_mov_b32_e32 v106, v0
	v_mov_b32_e32 v107, v0
	v_mov_b32_e32 v108, v0
	v_mov_b32_e32 v109, v0
	v_mov_b32_e32 v110, v0
	v_mov_b32_e32 v111, v0
	v_mov_b32_e32 v120, v0
	v_mov_b32_e32 v121, v0
	v_mov_b32_e32 v122, v0
	v_mov_b32_e32 v123, v0
	v_mov_b32_e32 v124, v0
	v_mov_b32_e32 v125, v0
	v_mov_b32_e32 v126, v0
	v_mov_b32_e32 v127, v0
	s_cmp_eq_u32 s100, 0
	s_cbranch_scc1 .LBB0_228
	ds_read_b128 v[128:131], v179
	ds_read_b128 v[132:135], v179 offset:1024
	ds_read_b128 v[136:139], v179 offset:2048
	ds_read_b128 v[140:143], v179 offset:3072
	ds_read_b128 v[162:165], v180
	ds_read_b128 v[166:169], v180 offset:1024
	ds_read_b128 v[170:173], v180 offset:2048
	ds_read_b128 v[186:189], v180 offset:3072
	s_add_u32 s8, s6, 0x10000
	s_addc_u32 s9, s7, 0
	s_cmp_eq_u32 s92, 12
	s_cselect_b32 s80, s69, s8
	s_cselect_b32 s81, s18, s9
	s_cselect_b32 s12, s77, vcc_lo
	s_cselect_b32 s13, s71, vcc_hi
	s_add_u32 s10, s80, 0x8000
	s_addc_u32 s11, s81, 0
	ds_read_b128 v[190:193], v181
	ds_read_b128 v[194:197], v181 offset:1024
	ds_read_b128 v[198:201], v181 offset:2048
	ds_read_b128 v[202:205], v181 offset:3072
	ds_read_b128 v[206:209], v181 offset:4096
	ds_read_b128 v[210:213], v181 offset:5120
	ds_read_b128 v[214:217], v181 offset:6144
	ds_read_b128 v[218:221], v181 offset:7168
	s_waitcnt vmcnt(16)
	s_waitcnt lgkmcnt(0)
	s_barrier
	s_setprio 1
	s_waitcnt lgkmcnt(0)
	v_mfma_f32_16x16x32_bf16 v[124:127], v[128:131], v[190:193], v[124:127]
	v_mfma_f32_16x16x32_bf16 v[120:123], v[136:139], v[190:193], v[120:123]
	v_mfma_f32_16x16x32_bf16 v[108:111], v[128:131], v[198:201], v[108:111]
	v_mfma_f32_16x16x32_bf16 v[104:107], v[136:139], v[198:201], v[104:107]
	v_mfma_f32_16x16x32_bf16 v[92:95], v[128:131], v[206:209], v[92:95]
	v_mfma_f32_16x16x32_bf16 v[88:91], v[136:139], v[206:209], v[88:91]
	v_mfma_f32_16x16x32_bf16 v[76:79], v[128:131], v[214:217], v[76:79]
	v_mfma_f32_16x16x32_bf16 v[72:75], v[136:139], v[214:217], v[72:75]
	v_mfma_f32_16x16x32_bf16 v[124:127], v[132:135], v[194:197], v[124:127]
	v_mfma_f32_16x16x32_bf16 v[120:123], v[140:143], v[194:197], v[120:123]
	v_mfma_f32_16x16x32_bf16 v[108:111], v[132:135], v[202:205], v[108:111]
	v_mfma_f32_16x16x32_bf16 v[104:107], v[140:143], v[202:205], v[104:107]
	v_mfma_f32_16x16x32_bf16 v[92:95], v[132:135], v[210:213], v[92:95]
	v_mfma_f32_16x16x32_bf16 v[88:91], v[140:143], v[210:213], v[88:91]
	v_mfma_f32_16x16x32_bf16 v[76:79], v[132:135], v[218:221], v[76:79]
	v_mfma_f32_16x16x32_bf16 v[72:75], v[140:143], v[218:221], v[72:75]
	s_setprio 0
	s_setprio 1
	v_mfma_f32_16x16x32_bf16 v[116:119], v[162:165], v[190:193], v[116:119]
	v_mfma_f32_16x16x32_bf16 v[112:115], v[170:173], v[190:193], v[112:115]
	v_mfma_f32_16x16x32_bf16 v[100:103], v[162:165], v[198:201], v[100:103]
	v_mfma_f32_16x16x32_bf16 v[96:99], v[170:173], v[198:201], v[96:99]
	v_mfma_f32_16x16x32_bf16 v[84:87], v[162:165], v[206:209], v[84:87]
	v_mfma_f32_16x16x32_bf16 v[80:83], v[170:173], v[206:209], v[80:83]
	v_mfma_f32_16x16x32_bf16 v[68:71], v[162:165], v[214:217], v[68:71]
	v_mfma_f32_16x16x32_bf16 v[64:67], v[170:173], v[214:217], v[64:67]
	v_mfma_f32_16x16x32_bf16 v[116:119], v[166:169], v[194:197], v[116:119]
	v_mfma_f32_16x16x32_bf16 v[112:115], v[186:189], v[194:197], v[112:115]
	v_mfma_f32_16x16x32_bf16 v[100:103], v[166:169], v[202:205], v[100:103]
	v_mfma_f32_16x16x32_bf16 v[96:99], v[186:189], v[202:205], v[96:99]
	v_mfma_f32_16x16x32_bf16 v[84:87], v[166:169], v[210:213], v[84:87]
	v_mfma_f32_16x16x32_bf16 v[80:83], v[186:189], v[210:213], v[80:83]
	v_mfma_f32_16x16x32_bf16 v[68:71], v[166:169], v[218:221], v[68:71]
	v_mfma_f32_16x16x32_bf16 v[64:67], v[186:189], v[218:221], v[64:67]
	s_setprio 0
	s_barrier
	s_add_i32 s6, s34, s84
	v_lshl_add_u64 v[174:175], s[12:13], 0, v[146:147]
	s_mov_b32 m0, s6
	ds_read_b128 v[190:193], v181 offset:16384
	ds_read_b128 v[194:197], v181 offset:17408
	ds_read_b128 v[198:201], v181 offset:18432
	ds_read_b128 v[202:205], v181 offset:19456
	ds_read_b128 v[206:209], v181 offset:20480
	ds_read_b128 v[210:213], v181 offset:21504
	ds_read_b128 v[214:217], v181 offset:22528
	ds_read_b128 v[218:221], v181 offset:23552
	global_load_lds_dwordx4 v[174:175], off
	s_add_i32 m0, s6, 0x2000
	s_add_u32 s6, s12, 0x40000
	v_lshl_add_u64 v[222:223], s[12:13], 0, v[150:151]
	s_addc_u32 s7, s13, 0
	s_add_i32 s38, s35, s84
	global_load_lds_dwordx4 v[222:223], off
	v_lshl_add_u64 v[224:225], s[6:7], 0, v[146:147]
	s_mov_b32 m0, s38
	s_nop 0
	global_load_lds_dwordx4 v[224:225], off
	v_lshl_add_u64 v[224:225], s[6:7], 0, v[150:151]
	s_add_i32 m0, s38, 0x2000
	s_nop 0
	global_load_lds_dwordx4 v[224:225], off
	v_lshl_add_u64 v[224:225], s[80:81], 0, v[144:145]
	s_mov_b32 m0, s79
	s_nop 0
	global_load_lds_dwordx4 v[224:225], off
	v_lshl_add_u64 v[224:225], s[80:81], 0, v[148:149]
	s_mov_b32 m0, s85
	s_nop 0
	global_load_lds_dwordx4 v[224:225], off
	s_waitcnt vmcnt(16)
	s_waitcnt lgkmcnt(0)
	s_barrier
	s_setprio 1
	s_waitcnt lgkmcnt(0)
	v_mfma_f32_16x16x32_bf16 v[60:63], v[128:131], v[190:193], v[60:63]
	v_mfma_f32_16x16x32_bf16 v[56:59], v[136:139], v[190:193], v[56:59]
	v_mfma_f32_16x16x32_bf16 v[44:47], v[128:131], v[198:201], v[44:47]
	v_mfma_f32_16x16x32_bf16 v[40:43], v[136:139], v[198:201], v[40:43]
	v_mfma_f32_16x16x32_bf16 v[28:31], v[128:131], v[206:209], v[28:31]
	v_mfma_f32_16x16x32_bf16 v[24:27], v[136:139], v[206:209], v[24:27]
	v_mfma_f32_16x16x32_bf16 v[12:15], v[128:131], v[214:217], v[12:15]
	v_mfma_f32_16x16x32_bf16 v[8:11], v[136:139], v[214:217], v[8:11]
	v_mfma_f32_16x16x32_bf16 v[60:63], v[132:135], v[194:197], v[60:63]
	v_mfma_f32_16x16x32_bf16 v[56:59], v[140:143], v[194:197], v[56:59]
	v_mfma_f32_16x16x32_bf16 v[44:47], v[132:135], v[202:205], v[44:47]
	v_mfma_f32_16x16x32_bf16 v[40:43], v[140:143], v[202:205], v[40:43]
	v_mfma_f32_16x16x32_bf16 v[28:31], v[132:135], v[210:213], v[28:31]
	v_mfma_f32_16x16x32_bf16 v[24:27], v[140:143], v[210:213], v[24:27]
	v_mfma_f32_16x16x32_bf16 v[12:15], v[132:135], v[218:221], v[12:15]
	v_mfma_f32_16x16x32_bf16 v[8:11], v[140:143], v[218:221], v[8:11]
	s_setprio 0
	s_setprio 1
	v_mfma_f32_16x16x32_bf16 v[52:55], v[162:165], v[190:193], v[52:55]
	v_mfma_f32_16x16x32_bf16 v[48:51], v[170:173], v[190:193], v[48:51]
	v_mfma_f32_16x16x32_bf16 v[36:39], v[162:165], v[198:201], v[36:39]
	v_mfma_f32_16x16x32_bf16 v[32:35], v[170:173], v[198:201], v[32:35]
	v_mfma_f32_16x16x32_bf16 v[20:23], v[162:165], v[206:209], v[20:23]
	v_mfma_f32_16x16x32_bf16 v[16:19], v[170:173], v[206:209], v[16:19]
	v_mfma_f32_16x16x32_bf16 v[4:7], v[162:165], v[214:217], v[4:7]
	v_mfma_f32_16x16x32_bf16 v[0:3], v[170:173], v[214:217], v[0:3]
	v_mfma_f32_16x16x32_bf16 v[52:55], v[166:169], v[194:197], v[52:55]
	v_mfma_f32_16x16x32_bf16 v[48:51], v[186:189], v[194:197], v[48:51]
	v_mfma_f32_16x16x32_bf16 v[36:39], v[166:169], v[202:205], v[36:39]
	v_mfma_f32_16x16x32_bf16 v[32:35], v[186:189], v[202:205], v[32:35]
	v_mfma_f32_16x16x32_bf16 v[20:23], v[166:169], v[210:213], v[20:23]
	v_mfma_f32_16x16x32_bf16 v[16:19], v[186:189], v[210:213], v[16:19]
	v_mfma_f32_16x16x32_bf16 v[4:7], v[166:169], v[218:221], v[4:7]
	v_mfma_f32_16x16x32_bf16 v[0:3], v[186:189], v[218:221], v[0:3]
	s_setprio 0
	s_barrier
	s_add_i32 s38, 0, 0x18000
	s_add_i32 s39, 0, 0x1c000
	v_add_u32_e32 v140, s38, v178
	v_add_u32_e32 v152, s39, v178
	ds_read_b128 v[128:131], v140
	ds_read_b128 v[132:135], v140 offset:1024
	ds_read_b128 v[136:139], v140 offset:2048
	ds_read_b128 v[140:143], v140 offset:3072
	ds_read_b128 v[162:165], v152
	ds_read_b128 v[166:169], v152 offset:1024
	ds_read_b128 v[170:173], v152 offset:2048
	ds_read_b128 v[186:189], v152 offset:3072
	s_add_u32 s6, s80, 0x4000
	s_addc_u32 s7, s81, 0
	s_mov_b32 m0, s86
	v_lshl_add_u64 v[224:225], s[6:7], 0, v[144:145]
	ds_read_b128 v[190:193], v181 offset:32768
	ds_read_b128 v[194:197], v181 offset:33792
	ds_read_b128 v[198:201], v181 offset:34816
	ds_read_b128 v[202:205], v181 offset:35840
	ds_read_b128 v[206:209], v181 offset:36864
	ds_read_b128 v[210:213], v181 offset:37888
	ds_read_b128 v[214:217], v181 offset:38912
	ds_read_b128 v[218:221], v181 offset:39936
	global_load_lds_dwordx4 v[224:225], off
	v_lshl_add_u64 v[224:225], s[6:7], 0, v[148:149]
	s_mov_b32 m0, s87
	s_nop 0
	global_load_lds_dwordx4 v[224:225], off
	s_waitcnt vmcnt(16)
	s_waitcnt lgkmcnt(0)
	s_barrier
	s_setprio 1
	s_waitcnt lgkmcnt(0)
	v_mfma_f32_16x16x32_bf16 v[124:127], v[128:131], v[190:193], v[124:127]
	v_mfma_f32_16x16x32_bf16 v[120:123], v[136:139], v[190:193], v[120:123]
	v_mfma_f32_16x16x32_bf16 v[108:111], v[128:131], v[198:201], v[108:111]
	v_mfma_f32_16x16x32_bf16 v[104:107], v[136:139], v[198:201], v[104:107]
	v_mfma_f32_16x16x32_bf16 v[92:95], v[128:131], v[206:209], v[92:95]
	v_mfma_f32_16x16x32_bf16 v[88:91], v[136:139], v[206:209], v[88:91]
	v_mfma_f32_16x16x32_bf16 v[76:79], v[128:131], v[214:217], v[76:79]
	v_mfma_f32_16x16x32_bf16 v[72:75], v[136:139], v[214:217], v[72:75]
	v_mfma_f32_16x16x32_bf16 v[124:127], v[132:135], v[194:197], v[124:127]
	v_mfma_f32_16x16x32_bf16 v[120:123], v[140:143], v[194:197], v[120:123]
	v_mfma_f32_16x16x32_bf16 v[108:111], v[132:135], v[202:205], v[108:111]
	v_mfma_f32_16x16x32_bf16 v[104:107], v[140:143], v[202:205], v[104:107]
	v_mfma_f32_16x16x32_bf16 v[92:95], v[132:135], v[210:213], v[92:95]
	v_mfma_f32_16x16x32_bf16 v[88:91], v[140:143], v[210:213], v[88:91]
	v_mfma_f32_16x16x32_bf16 v[76:79], v[132:135], v[218:221], v[76:79]
	v_mfma_f32_16x16x32_bf16 v[72:75], v[140:143], v[218:221], v[72:75]
	s_setprio 0
	s_setprio 1
	v_mfma_f32_16x16x32_bf16 v[116:119], v[162:165], v[190:193], v[116:119]
	v_mfma_f32_16x16x32_bf16 v[112:115], v[170:173], v[190:193], v[112:115]
	v_mfma_f32_16x16x32_bf16 v[100:103], v[162:165], v[198:201], v[100:103]
	v_mfma_f32_16x16x32_bf16 v[96:99], v[170:173], v[198:201], v[96:99]
	v_mfma_f32_16x16x32_bf16 v[84:87], v[162:165], v[206:209], v[84:87]
	v_mfma_f32_16x16x32_bf16 v[80:83], v[170:173], v[206:209], v[80:83]
	v_mfma_f32_16x16x32_bf16 v[68:71], v[162:165], v[214:217], v[68:71]
	v_mfma_f32_16x16x32_bf16 v[64:67], v[170:173], v[214:217], v[64:67]
	v_mfma_f32_16x16x32_bf16 v[116:119], v[166:169], v[194:197], v[116:119]
	v_mfma_f32_16x16x32_bf16 v[112:115], v[186:189], v[194:197], v[112:115]
	v_mfma_f32_16x16x32_bf16 v[100:103], v[166:169], v[202:205], v[100:103]
	v_mfma_f32_16x16x32_bf16 v[96:99], v[186:189], v[202:205], v[96:99]
	v_mfma_f32_16x16x32_bf16 v[84:87], v[166:169], v[210:213], v[84:87]
	v_mfma_f32_16x16x32_bf16 v[80:83], v[186:189], v[210:213], v[80:83]
	v_mfma_f32_16x16x32_bf16 v[68:71], v[166:169], v[218:221], v[68:71]
	v_mfma_f32_16x16x32_bf16 v[64:67], v[186:189], v[218:221], v[64:67]
	s_setprio 0
	s_barrier
	s_add_i32 s6, s38, s84
	v_lshl_add_u64 v[174:175], v[174:175], 0, s[48:49]
	s_mov_b32 m0, s6
	ds_read_b128 v[190:193], v181 offset:49152
	ds_read_b128 v[194:197], v181 offset:50176
	ds_read_b128 v[198:201], v181 offset:51200
	ds_read_b128 v[202:205], v181 offset:52224
	ds_read_b128 v[206:209], v181 offset:53248
	ds_read_b128 v[210:213], v181 offset:54272
	ds_read_b128 v[214:217], v181 offset:55296
	ds_read_b128 v[218:221], v181 offset:56320
	global_load_lds_dwordx4 v[174:175], off
	s_add_i32 m0, s6, 0x2000
	s_add_u32 s6, s12, 0x40080
	v_lshl_add_u64 v[174:175], v[222:223], 0, s[48:49]
	s_addc_u32 s7, s13, 0
	s_add_i32 s12, s39, s84
	global_load_lds_dwordx4 v[174:175], off
	v_lshl_add_u64 v[174:175], s[6:7], 0, v[146:147]
	s_mov_b32 m0, s12
	s_nop 0
	global_load_lds_dwordx4 v[174:175], off
	v_lshl_add_u64 v[174:175], s[6:7], 0, v[150:151]
	s_add_i32 m0, s12, 0x2000
	s_nop 0
	global_load_lds_dwordx4 v[174:175], off
	v_lshl_add_u64 v[174:175], s[10:11], 0, v[144:145]
	s_mov_b32 m0, s33
	s_nop 0
	global_load_lds_dwordx4 v[174:175], off
	v_lshl_add_u64 v[174:175], s[10:11], 0, v[148:149]
	s_mov_b32 m0, s56
	s_nop 0
	global_load_lds_dwordx4 v[174:175], off
	s_waitcnt vmcnt(8)
	s_waitcnt lgkmcnt(0)
	s_barrier
	s_setprio 1
	s_waitcnt lgkmcnt(0)
	v_mfma_f32_16x16x32_bf16 v[60:63], v[128:131], v[190:193], v[60:63]
	v_mfma_f32_16x16x32_bf16 v[56:59], v[136:139], v[190:193], v[56:59]
	v_mfma_f32_16x16x32_bf16 v[44:47], v[128:131], v[198:201], v[44:47]
	v_mfma_f32_16x16x32_bf16 v[40:43], v[136:139], v[198:201], v[40:43]
	v_mfma_f32_16x16x32_bf16 v[28:31], v[128:131], v[206:209], v[28:31]
	v_mfma_f32_16x16x32_bf16 v[24:27], v[136:139], v[206:209], v[24:27]
	v_mfma_f32_16x16x32_bf16 v[12:15], v[128:131], v[214:217], v[12:15]
	v_mfma_f32_16x16x32_bf16 v[8:11], v[136:139], v[214:217], v[8:11]
	v_mfma_f32_16x16x32_bf16 v[60:63], v[132:135], v[194:197], v[60:63]
	v_mfma_f32_16x16x32_bf16 v[56:59], v[140:143], v[194:197], v[56:59]
	v_mfma_f32_16x16x32_bf16 v[44:47], v[132:135], v[202:205], v[44:47]
	v_mfma_f32_16x16x32_bf16 v[40:43], v[140:143], v[202:205], v[40:43]
	v_mfma_f32_16x16x32_bf16 v[28:31], v[132:135], v[210:213], v[28:31]
	v_mfma_f32_16x16x32_bf16 v[24:27], v[140:143], v[210:213], v[24:27]
	v_mfma_f32_16x16x32_bf16 v[12:15], v[132:135], v[218:221], v[12:15]
	v_mfma_f32_16x16x32_bf16 v[8:11], v[140:143], v[218:221], v[8:11]
	s_setprio 0
	s_setprio 1
	v_mfma_f32_16x16x32_bf16 v[52:55], v[162:165], v[190:193], v[52:55]
	v_mfma_f32_16x16x32_bf16 v[48:51], v[170:173], v[190:193], v[48:51]
	v_mfma_f32_16x16x32_bf16 v[36:39], v[162:165], v[198:201], v[36:39]
	v_mfma_f32_16x16x32_bf16 v[32:35], v[170:173], v[198:201], v[32:35]
	v_mfma_f32_16x16x32_bf16 v[20:23], v[162:165], v[206:209], v[20:23]
	v_mfma_f32_16x16x32_bf16 v[16:19], v[170:173], v[206:209], v[16:19]
	v_mfma_f32_16x16x32_bf16 v[4:7], v[162:165], v[214:217], v[4:7]
	v_mfma_f32_16x16x32_bf16 v[0:3], v[170:173], v[214:217], v[0:3]
	v_mfma_f32_16x16x32_bf16 v[52:55], v[166:169], v[194:197], v[52:55]
	v_mfma_f32_16x16x32_bf16 v[48:51], v[186:189], v[194:197], v[48:51]
	v_mfma_f32_16x16x32_bf16 v[36:39], v[166:169], v[202:205], v[36:39]
	v_mfma_f32_16x16x32_bf16 v[32:35], v[186:189], v[202:205], v[32:35]
	v_mfma_f32_16x16x32_bf16 v[20:23], v[166:169], v[210:213], v[20:23]
	v_mfma_f32_16x16x32_bf16 v[16:19], v[186:189], v[210:213], v[16:19]
	v_mfma_f32_16x16x32_bf16 v[4:7], v[166:169], v[218:221], v[4:7]
	v_mfma_f32_16x16x32_bf16 v[0:3], v[186:189], v[218:221], v[0:3]
	s_setprio 0
	s_barrier
	s_add_i32 s92, s92, 2
	s_add_u32 vcc_lo, vcc_lo, 0x100
	s_addc_u32 vcc_hi, vcc_hi, 0
	s_cmp_gt_u32 s92, 13
	s_mov_b64 s[6:7], s[8:9]

.LBB0_231:
	s_mov_b32 s98, s69
	s_mov_b32 s99, s18
	v_lshl_add_u64 v[174:175], s[98:99], 0, v[154:155]
	s_add_i32 m0, s79, 0xc000
	s_nop 0
	global_load_lds_dwordx4 v[174:175], off
	v_lshl_add_u64 v[174:175], s[98:99], 0, v[156:157]
	s_add_i32 m0, s79, 0xe000
	s_nop 0
	global_load_lds_dwordx4 v[174:175], off
	s_mov_b32 s100, 1
	v_mov_b32_e32 v185, v177
	v_mov_b32_e32 v186, v176
	s_cmp_gt_i32 s78, 3
	v_add_u32_e32 v162, s96, v186
	v_lshlrev_b32_e32 v164, 3, v185
	s_mov_b64 s[6:7], -1
	s_cbranch_scc1 .LBB0_234
	s_andn2_b64 vcc, exec, s[6:7]
	s_cbranch_vccz .LBB0_288

.LBB0_280:
	s_or_b64 exec, exec, s[8:9]
	s_add_i32 s8, s78, -16
	s_lshl_b32 s9, s78, 6
	s_lshr_b32 s60, s8, 2
	s_and_b32 s9, s9, 0x80
	v_readlane_b32 s10, v251, 33
	s_lshl_b32 s8, s60, 8
	s_or_b32 s9, s9, s10
	s_or_b32 s8, s9, s8
	v_add_u32_e32 v152, s8, v164
	s_lshl_b32 s8, s78, 2
	v_and_or_b32 v166, s8, 4, v152
	v_ashrrev_i32_e32 v167, 31, v166
	v_readlane_b32 s12, v251, 2
	v_lshlrev_b64 v[136:137], 2, v[166:167]
	v_readlane_b32 s13, v251, 3
	v_lshl_add_u64 v[132:133], s[44:45], 0, v[136:137]
	s_waitcnt lgkmcnt(0)
	v_lshl_add_u64 v[128:129], s[12:13], 0, v[136:137]
	v_lshl_add_u64 v[136:137], s[46:47], 0, v[136:137]
	s_barrier
	global_load_dwordx4 v[128:131], v[128:129], off
	s_nop 0
	global_load_dwordx4 v[132:135], v[132:133], off
	v_lshlrev_b32_e32 v141, 6, v186
	global_load_dwordx4 v[136:139], v[136:137], off
	v_mov_b32_e32 v140, 0
	s_andn2_b64 vcc, exec, s[0:1]
	v_add_u32_e32 v172, s63, v165
	v_and_b32_e32 v173, 64, v141
	v_mov_b32_e32 v141, 0
	v_mov_b32_e32 v142, 0
	v_mov_b32_e32 v143, 0
	v_readlane_b32 s14, v251, 4
	v_readlane_b32 s15, v251, 5
	v_readlane_b32 s16, v251, 6
	v_readlane_b32 s17, v251, 7
	v_readlane_b32 s18, v251, 8
	v_readlane_b32 s19, v251, 9
	v_readlane_b32 s20, v251, 10
	v_readlane_b32 s21, v251, 11
	v_readlane_b32 s22, v251, 12
	v_readlane_b32 s23, v251, 13
	v_readlane_b32 s24, v251, 14
	v_readlane_b32 s25, v251, 15
	v_readlane_b32 s26, v251, 16
	v_readlane_b32 s27, v251, 17
	s_cbranch_vccnz .LBB0_282
	v_lshlrev_b32_e32 v140, 4, v185
	v_add3_u32 v140, v172, v173, v140
	ds_read_b128 v[140:143], v140

	.amdhsa_kernel _Z7hyb_fwd4Args
		.amdhsa_group_segment_fixed_size 0
		.amdhsa_private_segment_fixed_size 0
		.amdhsa_kernarg_size 416
		.amdhsa_user_sgpr_count 2
		.amdhsa_user_sgpr_dispatch_ptr 0
		.amdhsa_user_sgpr_queue_ptr 0
		.amdhsa_user_sgpr_kernarg_segment_ptr 1
		.amdhsa_user_sgpr_dispatch_id 0
		.amdhsa_user_sgpr_kernarg_preload_length 0
		.amdhsa_user_sgpr_kernarg_preload_offset 0
		.amdhsa_user_sgpr_private_segment_size 0
		.amdhsa_uses_dynamic_stack 0
		.amdhsa_enable_private_segment 0
		.amdhsa_system_sgpr_workgroup_id_x 1
		.amdhsa_system_sgpr_workgroup_id_y 0
		.amdhsa_system_sgpr_workgroup_id_z 0
		.amdhsa_system_sgpr_workgroup_info 0
		.amdhsa_system_vgpr_workitem_id 0
		.amdhsa_next_free_vgpr 252
		.amdhsa_next_free_sgpr 102
		.amdhsa_accum_offset 252
		.amdhsa_reserve_vcc 1
		.amdhsa_float_round_mode_32 0
		.amdhsa_float_round_mode_16_64 0
		.amdhsa_float_denorm_mode_32 3
		.amdhsa_float_denorm_mode_16_64 3
		.amdhsa_dx10_clamp 1
		.amdhsa_ieee_mode 1
		.amdhsa_fp16_overflow 0
		.amdhsa_tg_split 0
		.amdhsa_exception_fp_ieee_invalid_op 0
		.amdhsa_exception_fp_denorm_src 0
		.amdhsa_exception_fp_ieee_div_zero 0
		.amdhsa_exception_fp_ieee_overflow 0
		.amdhsa_exception_fp_ieee_underflow 0
		.amdhsa_exception_fp_ieee_inexact 0
		.amdhsa_exception_int_div_zero 0
	.end_amdhsa_kernel
